# P5 mid-K gate rescale with 16 gate loads in flight (8 register slots refilled as consumed) instead of one load pair per wait
# speedup vs baseline: 1.0265x; 1.0027x over previous
.LBB0_703:
	s_cmpk_lg_i32 s48, 0x400
	s_cbranch_scc1 .LBB0_702
	v_lshlrev_b32_e32 v208, 12, v155
	v_lshl_add_u32 v208, v154, 1, v208
	s_mov_b64 s[20:21], s[26:27]
	global_load_dwordx4 v[168:171], v208, s[20:21]
	global_load_dwordx4 v[172:175], v208, s[20:21] offset:2048
	global_load_dwordx4 v[176:179], v208, s[20:21] offset:64
	global_load_dwordx4 v[180:183], v208, s[20:21] offset:2112
	s_add_u32 s20, s26, 0x10000
	s_addc_u32 s21, s27, 0
	global_load_dwordx4 v[184:187], v208, s[20:21]
	global_load_dwordx4 v[188:191], v208, s[20:21] offset:2048
	global_load_dwordx4 v[192:195], v208, s[20:21] offset:64
	global_load_dwordx4 v[196:199], v208, s[20:21] offset:2112
	s_add_u32 s20, s26, 0x20000
	s_addc_u32 s21, s27, 0
	global_load_dwordx4 v[200:203], v208, s[20:21]
	global_load_dwordx4 v[204:207], v208, s[20:21] offset:2048
	global_load_dwordx4 v[218:221], v208, s[20:21] offset:64
	global_load_dwordx4 v[222:225], v208, s[20:21] offset:2112
	s_add_u32 s20, s26, 0x30000
	s_addc_u32 s21, s27, 0
	global_load_dwordx4 v[226:229], v208, s[20:21]
	global_load_dwordx4 v[230:233], v208, s[20:21] offset:2048
	global_load_dwordx4 v[234:237], v208, s[20:21] offset:64
	global_load_dwordx4 v[238:241], v208, s[20:21] offset:2112
	s_waitcnt vmcnt(14)
	v_lshlrev_b32_e32 v128, 16, v172
	v_and_b32_e32 v129, 0xffff0000, v172
	v_lshlrev_b32_e32 v130, 16, v173
	v_and_b32_e32 v131, 0xffff0000, v173
	v_lshlrev_b32_e32 v132, 16, v174
	v_and_b32_e32 v133, 0xffff0000, v174
	v_lshlrev_b32_e32 v134, 16, v175
	v_and_b32_e32 v135, 0xffff0000, v175
	v_max_f32_e32 v128, 0xda24260, v128
	v_max_f32_e32 v129, 0xda24260, v129
	v_max_f32_e32 v130, 0xda24260, v130
	v_max_f32_e32 v131, 0xda24260, v131
	v_max_f32_e32 v132, 0xda24260, v132
	v_max_f32_e32 v133, 0xda24260, v133
	v_max_f32_e32 v134, 0xda24260, v134
	v_max_f32_e32 v135, 0xda24260, v135
	v_rcp_f32_e32 v128, v128
	v_rcp_f32_e32 v129, v129
	v_rcp_f32_e32 v130, v130
	v_rcp_f32_e32 v131, v131
	v_rcp_f32_e32 v132, v132
	v_rcp_f32_e32 v133, v133
	v_rcp_f32_e32 v134, v134
	v_rcp_f32_e32 v135, v135
	v_and_b32_e32 v175, 0xffff0000, v171
	v_lshlrev_b32_e32 v174, 16, v171
	v_and_b32_e32 v173, 0xffff0000, v170
	v_lshlrev_b32_e32 v172, 16, v170
	v_and_b32_e32 v171, 0xffff0000, v169
	v_lshlrev_b32_e32 v170, 16, v169
	v_and_b32_e32 v169, 0xffff0000, v168
	v_lshlrev_b32_e32 v168, 16, v168
	v_pk_mul_f32 v[168:169], v[128:129], v[168:169]
	v_pk_mul_f32 v[170:171], v[130:131], v[170:171]
	v_pk_mul_f32 v[172:173], v[132:133], v[172:173]
	v_pk_mul_f32 v[174:175], v[134:135], v[174:175]
	v_pk_mul_f32 v[124:125], v[124:125], v[168:169]
	v_pk_mul_f32 v[126:127], v[126:127], v[170:171]
	v_pk_mul_f32 v[120:121], v[120:121], v[172:173]
	v_pk_mul_f32 v[122:123], v[122:123], v[174:175]
	s_add_u32 s20, s26, 0x80000
	s_addc_u32 s21, s27, 0
	global_load_dwordx4 v[168:171], v208, s[20:21]
	global_load_dwordx4 v[172:175], v208, s[20:21] offset:2048
	s_waitcnt vmcnt(14)
	v_lshlrev_b32_e32 v128, 16, v180
	v_and_b32_e32 v129, 0xffff0000, v180
	v_lshlrev_b32_e32 v130, 16, v181
	v_and_b32_e32 v131, 0xffff0000, v181
	v_lshlrev_b32_e32 v132, 16, v182
	v_and_b32_e32 v133, 0xffff0000, v182
	v_lshlrev_b32_e32 v134, 16, v183
	v_and_b32_e32 v135, 0xffff0000, v183
	v_max_f32_e32 v128, 0xda24260, v128
	v_max_f32_e32 v129, 0xda24260, v129
	v_max_f32_e32 v130, 0xda24260, v130
	v_max_f32_e32 v131, 0xda24260, v131
	v_max_f32_e32 v132, 0xda24260, v132
	v_max_f32_e32 v133, 0xda24260, v133
	v_max_f32_e32 v134, 0xda24260, v134
	v_max_f32_e32 v135, 0xda24260, v135
	v_rcp_f32_e32 v128, v128
	v_rcp_f32_e32 v129, v129
	v_rcp_f32_e32 v130, v130
	v_rcp_f32_e32 v131, v131
	v_rcp_f32_e32 v132, v132
	v_rcp_f32_e32 v133, v133
	v_rcp_f32_e32 v134, v134
	v_rcp_f32_e32 v135, v135
	v_and_b32_e32 v183, 0xffff0000, v179
	v_lshlrev_b32_e32 v182, 16, v179
	v_and_b32_e32 v181, 0xffff0000, v178
	v_lshlrev_b32_e32 v180, 16, v178
	v_and_b32_e32 v179, 0xffff0000, v177
	v_lshlrev_b32_e32 v178, 16, v177
	v_and_b32_e32 v177, 0xffff0000, v176
	v_lshlrev_b32_e32 v176, 16, v176
	v_pk_mul_f32 v[176:177], v[128:129], v[176:177]
	v_pk_mul_f32 v[178:179], v[130:131], v[178:179]
	v_pk_mul_f32 v[180:181], v[132:133], v[180:181]
	v_pk_mul_f32 v[182:183], v[134:135], v[182:183]
	v_pk_mul_f32 v[116:117], v[116:117], v[176:177]
	v_pk_mul_f32 v[118:119], v[118:119], v[178:179]
	v_pk_mul_f32 v[112:113], v[112:113], v[180:181]
	v_pk_mul_f32 v[114:115], v[114:115], v[182:183]
	global_load_dwordx4 v[176:179], v208, s[20:21] offset:64
	global_load_dwordx4 v[180:183], v208, s[20:21] offset:2112
	s_waitcnt vmcnt(14)
	v_lshlrev_b32_e32 v128, 16, v188
	v_and_b32_e32 v129, 0xffff0000, v188
	v_lshlrev_b32_e32 v130, 16, v189
	v_and_b32_e32 v131, 0xffff0000, v189
	v_lshlrev_b32_e32 v132, 16, v190
	v_and_b32_e32 v133, 0xffff0000, v190
	v_lshlrev_b32_e32 v134, 16, v191
	v_and_b32_e32 v135, 0xffff0000, v191
	v_max_f32_e32 v128, 0xda24260, v128
	v_max_f32_e32 v129, 0xda24260, v129
	v_max_f32_e32 v130, 0xda24260, v130
	v_max_f32_e32 v131, 0xda24260, v131
	v_max_f32_e32 v132, 0xda24260, v132
	v_max_f32_e32 v133, 0xda24260, v133
	v_max_f32_e32 v134, 0xda24260, v134
	v_max_f32_e32 v135, 0xda24260, v135
	v_rcp_f32_e32 v128, v128
	v_rcp_f32_e32 v129, v129
	v_rcp_f32_e32 v130, v130
	v_rcp_f32_e32 v131, v131
	v_rcp_f32_e32 v132, v132
	v_rcp_f32_e32 v133, v133
	v_rcp_f32_e32 v134, v134
	v_rcp_f32_e32 v135, v135
	v_and_b32_e32 v191, 0xffff0000, v187
	v_lshlrev_b32_e32 v190, 16, v187
	v_and_b32_e32 v189, 0xffff0000, v186
	v_lshlrev_b32_e32 v188, 16, v186
	v_and_b32_e32 v187, 0xffff0000, v185
	v_lshlrev_b32_e32 v186, 16, v185
	v_and_b32_e32 v185, 0xffff0000, v184
	v_lshlrev_b32_e32 v184, 16, v184
	v_pk_mul_f32 v[184:185], v[128:129], v[184:185]
	v_pk_mul_f32 v[186:187], v[130:131], v[186:187]
	v_pk_mul_f32 v[188:189], v[132:133], v[188:189]
	v_pk_mul_f32 v[190:191], v[134:135], v[190:191]
	v_pk_mul_f32 v[108:109], v[108:109], v[184:185]
	v_pk_mul_f32 v[110:111], v[110:111], v[186:187]
	v_pk_mul_f32 v[104:105], v[104:105], v[188:189]
	v_pk_mul_f32 v[106:107], v[106:107], v[190:191]
	s_add_u32 s20, s26, 0x90000
	s_addc_u32 s21, s27, 0
	global_load_dwordx4 v[184:187], v208, s[20:21]
	global_load_dwordx4 v[188:191], v208, s[20:21] offset:2048
	s_waitcnt vmcnt(14)
	v_lshlrev_b32_e32 v128, 16, v196
	v_and_b32_e32 v129, 0xffff0000, v196
	v_lshlrev_b32_e32 v130, 16, v197
	v_and_b32_e32 v131, 0xffff0000, v197
	v_lshlrev_b32_e32 v132, 16, v198
	v_and_b32_e32 v133, 0xffff0000, v198
	v_lshlrev_b32_e32 v134, 16, v199
	v_and_b32_e32 v135, 0xffff0000, v199
	v_max_f32_e32 v128, 0xda24260, v128
	v_max_f32_e32 v129, 0xda24260, v129
	v_max_f32_e32 v130, 0xda24260, v130
	v_max_f32_e32 v131, 0xda24260, v131
	v_max_f32_e32 v132, 0xda24260, v132
	v_max_f32_e32 v133, 0xda24260, v133
	v_max_f32_e32 v134, 0xda24260, v134
	v_max_f32_e32 v135, 0xda24260, v135
	v_rcp_f32_e32 v128, v128
	v_rcp_f32_e32 v129, v129
	v_rcp_f32_e32 v130, v130
	v_rcp_f32_e32 v131, v131
	v_rcp_f32_e32 v132, v132
	v_rcp_f32_e32 v133, v133
	v_rcp_f32_e32 v134, v134
	v_rcp_f32_e32 v135, v135
	v_and_b32_e32 v199, 0xffff0000, v195
	v_lshlrev_b32_e32 v198, 16, v195
	v_and_b32_e32 v197, 0xffff0000, v194
	v_lshlrev_b32_e32 v196, 16, v194
	v_and_b32_e32 v195, 0xffff0000, v193
	v_lshlrev_b32_e32 v194, 16, v193
	v_and_b32_e32 v193, 0xffff0000, v192
	v_lshlrev_b32_e32 v192, 16, v192
	v_pk_mul_f32 v[192:193], v[128:129], v[192:193]
	v_pk_mul_f32 v[194:195], v[130:131], v[194:195]
	v_pk_mul_f32 v[196:197], v[132:133], v[196:197]
	v_pk_mul_f32 v[198:199], v[134:135], v[198:199]
	v_pk_mul_f32 v[100:101], v[100:101], v[192:193]
	v_pk_mul_f32 v[102:103], v[102:103], v[194:195]
	v_pk_mul_f32 v[96:97], v[96:97], v[196:197]
	v_pk_mul_f32 v[98:99], v[98:99], v[198:199]
	global_load_dwordx4 v[192:195], v208, s[20:21] offset:64
	global_load_dwordx4 v[196:199], v208, s[20:21] offset:2112
	s_waitcnt vmcnt(14)
	v_lshlrev_b32_e32 v128, 16, v204
	v_and_b32_e32 v129, 0xffff0000, v204
	v_lshlrev_b32_e32 v130, 16, v205
	v_and_b32_e32 v131, 0xffff0000, v205
	v_lshlrev_b32_e32 v132, 16, v206
	v_and_b32_e32 v133, 0xffff0000, v206
	v_lshlrev_b32_e32 v134, 16, v207
	v_and_b32_e32 v135, 0xffff0000, v207
	v_max_f32_e32 v128, 0xda24260, v128
	v_max_f32_e32 v129, 0xda24260, v129
	v_max_f32_e32 v130, 0xda24260, v130
	v_max_f32_e32 v131, 0xda24260, v131
	v_max_f32_e32 v132, 0xda24260, v132
	v_max_f32_e32 v133, 0xda24260, v133
	v_max_f32_e32 v134, 0xda24260, v134
	v_max_f32_e32 v135, 0xda24260, v135
	v_rcp_f32_e32 v128, v128
	v_rcp_f32_e32 v129, v129
	v_rcp_f32_e32 v130, v130
	v_rcp_f32_e32 v131, v131
	v_rcp_f32_e32 v132, v132
	v_rcp_f32_e32 v133, v133
	v_rcp_f32_e32 v134, v134
	v_rcp_f32_e32 v135, v135
	v_and_b32_e32 v207, 0xffff0000, v203
	v_lshlrev_b32_e32 v206, 16, v203
	v_and_b32_e32 v205, 0xffff0000, v202
	v_lshlrev_b32_e32 v204, 16, v202
	v_and_b32_e32 v203, 0xffff0000, v201
	v_lshlrev_b32_e32 v202, 16, v201
	v_and_b32_e32 v201, 0xffff0000, v200
	v_lshlrev_b32_e32 v200, 16, v200
	v_pk_mul_f32 v[200:201], v[128:129], v[200:201]
	v_pk_mul_f32 v[202:203], v[130:131], v[202:203]
	v_pk_mul_f32 v[204:205], v[132:133], v[204:205]
	v_pk_mul_f32 v[206:207], v[134:135], v[206:207]
	v_pk_mul_f32 v[92:93], v[92:93], v[200:201]
	v_pk_mul_f32 v[94:95], v[94:95], v[202:203]
	v_pk_mul_f32 v[88:89], v[88:89], v[204:205]
	v_pk_mul_f32 v[90:91], v[90:91], v[206:207]
	s_add_u32 s20, s26, 0xa0000
	s_addc_u32 s21, s27, 0
	global_load_dwordx4 v[200:203], v208, s[20:21]
	global_load_dwordx4 v[204:207], v208, s[20:21] offset:2048
	s_waitcnt vmcnt(14)
	v_lshlrev_b32_e32 v128, 16, v222
	v_and_b32_e32 v129, 0xffff0000, v222
	v_lshlrev_b32_e32 v130, 16, v223
	v_and_b32_e32 v131, 0xffff0000, v223
	v_lshlrev_b32_e32 v132, 16, v224
	v_and_b32_e32 v133, 0xffff0000, v224
	v_lshlrev_b32_e32 v134, 16, v225
	v_and_b32_e32 v135, 0xffff0000, v225
	v_max_f32_e32 v128, 0xda24260, v128
	v_max_f32_e32 v129, 0xda24260, v129
	v_max_f32_e32 v130, 0xda24260, v130
	v_max_f32_e32 v131, 0xda24260, v131
	v_max_f32_e32 v132, 0xda24260, v132
	v_max_f32_e32 v133, 0xda24260, v133
	v_max_f32_e32 v134, 0xda24260, v134
	v_max_f32_e32 v135, 0xda24260, v135
	v_rcp_f32_e32 v128, v128
	v_rcp_f32_e32 v129, v129
	v_rcp_f32_e32 v130, v130
	v_rcp_f32_e32 v131, v131
	v_rcp_f32_e32 v132, v132
	v_rcp_f32_e32 v133, v133
	v_rcp_f32_e32 v134, v134
	v_rcp_f32_e32 v135, v135
	v_and_b32_e32 v225, 0xffff0000, v221
	v_lshlrev_b32_e32 v224, 16, v221
	v_and_b32_e32 v223, 0xffff0000, v220
	v_lshlrev_b32_e32 v222, 16, v220
	v_and_b32_e32 v221, 0xffff0000, v219
	v_lshlrev_b32_e32 v220, 16, v219
	v_and_b32_e32 v219, 0xffff0000, v218
	v_lshlrev_b32_e32 v218, 16, v218
	v_pk_mul_f32 v[218:219], v[128:129], v[218:219]
	v_pk_mul_f32 v[220:221], v[130:131], v[220:221]
	v_pk_mul_f32 v[222:223], v[132:133], v[222:223]
	v_pk_mul_f32 v[224:225], v[134:135], v[224:225]
	v_pk_mul_f32 v[84:85], v[84:85], v[218:219]
	v_pk_mul_f32 v[86:87], v[86:87], v[220:221]
	v_pk_mul_f32 v[80:81], v[80:81], v[222:223]
	v_pk_mul_f32 v[82:83], v[82:83], v[224:225]
	global_load_dwordx4 v[218:221], v208, s[20:21] offset:64
	global_load_dwordx4 v[222:225], v208, s[20:21] offset:2112
	s_waitcnt vmcnt(14)
	v_lshlrev_b32_e32 v128, 16, v230
	v_and_b32_e32 v129, 0xffff0000, v230
	v_lshlrev_b32_e32 v130, 16, v231
	v_and_b32_e32 v131, 0xffff0000, v231
	v_lshlrev_b32_e32 v132, 16, v232
	v_and_b32_e32 v133, 0xffff0000, v232
	v_lshlrev_b32_e32 v134, 16, v233
	v_and_b32_e32 v135, 0xffff0000, v233
	v_max_f32_e32 v128, 0xda24260, v128
	v_max_f32_e32 v129, 0xda24260, v129
	v_max_f32_e32 v130, 0xda24260, v130
	v_max_f32_e32 v131, 0xda24260, v131
	v_max_f32_e32 v132, 0xda24260, v132
	v_max_f32_e32 v133, 0xda24260, v133
	v_max_f32_e32 v134, 0xda24260, v134
	v_max_f32_e32 v135, 0xda24260, v135
	v_rcp_f32_e32 v128, v128
	v_rcp_f32_e32 v129, v129
	v_rcp_f32_e32 v130, v130
	v_rcp_f32_e32 v131, v131
	v_rcp_f32_e32 v132, v132
	v_rcp_f32_e32 v133, v133
	v_rcp_f32_e32 v134, v134
	v_rcp_f32_e32 v135, v135
	v_and_b32_e32 v233, 0xffff0000, v229
	v_lshlrev_b32_e32 v232, 16, v229
	v_and_b32_e32 v231, 0xffff0000, v228
	v_lshlrev_b32_e32 v230, 16, v228
	v_and_b32_e32 v229, 0xffff0000, v227
	v_lshlrev_b32_e32 v228, 16, v227
	v_and_b32_e32 v227, 0xffff0000, v226
	v_lshlrev_b32_e32 v226, 16, v226
	v_pk_mul_f32 v[226:227], v[128:129], v[226:227]
	v_pk_mul_f32 v[228:229], v[130:131], v[228:229]
	v_pk_mul_f32 v[230:231], v[132:133], v[230:231]
	v_pk_mul_f32 v[232:233], v[134:135], v[232:233]
	v_pk_mul_f32 v[76:77], v[76:77], v[226:227]
	v_pk_mul_f32 v[78:79], v[78:79], v[228:229]
	v_pk_mul_f32 v[72:73], v[72:73], v[230:231]
	v_pk_mul_f32 v[74:75], v[74:75], v[232:233]
	s_add_u32 s20, s26, 0xb0000
	s_addc_u32 s21, s27, 0
	global_load_dwordx4 v[226:229], v208, s[20:21]
	global_load_dwordx4 v[230:233], v208, s[20:21] offset:2048
	s_waitcnt vmcnt(14)
	v_lshlrev_b32_e32 v128, 16, v238
	v_and_b32_e32 v129, 0xffff0000, v238
	v_lshlrev_b32_e32 v130, 16, v239
	v_and_b32_e32 v131, 0xffff0000, v239
	v_lshlrev_b32_e32 v132, 16, v240
	v_and_b32_e32 v133, 0xffff0000, v240
	v_lshlrev_b32_e32 v134, 16, v241
	v_and_b32_e32 v135, 0xffff0000, v241
	v_max_f32_e32 v128, 0xda24260, v128
	v_max_f32_e32 v129, 0xda24260, v129
	v_max_f32_e32 v130, 0xda24260, v130
	v_max_f32_e32 v131, 0xda24260, v131
	v_max_f32_e32 v132, 0xda24260, v132
	v_max_f32_e32 v133, 0xda24260, v133
	v_max_f32_e32 v134, 0xda24260, v134
	v_max_f32_e32 v135, 0xda24260, v135
	v_rcp_f32_e32 v128, v128
	v_rcp_f32_e32 v129, v129
	v_rcp_f32_e32 v130, v130
	v_rcp_f32_e32 v131, v131
	v_rcp_f32_e32 v132, v132
	v_rcp_f32_e32 v133, v133
	v_rcp_f32_e32 v134, v134
	v_rcp_f32_e32 v135, v135
	v_and_b32_e32 v241, 0xffff0000, v237
	v_lshlrev_b32_e32 v240, 16, v237
	v_and_b32_e32 v239, 0xffff0000, v236
	v_lshlrev_b32_e32 v238, 16, v236
	v_and_b32_e32 v237, 0xffff0000, v235
	v_lshlrev_b32_e32 v236, 16, v235
	v_and_b32_e32 v235, 0xffff0000, v234
	v_lshlrev_b32_e32 v234, 16, v234
	v_pk_mul_f32 v[234:235], v[128:129], v[234:235]
	v_pk_mul_f32 v[236:237], v[130:131], v[236:237]
	v_pk_mul_f32 v[238:239], v[132:133], v[238:239]
	v_pk_mul_f32 v[240:241], v[134:135], v[240:241]
	v_pk_mul_f32 v[68:69], v[68:69], v[234:235]
	v_pk_mul_f32 v[70:71], v[70:71], v[236:237]
	v_pk_mul_f32 v[64:65], v[64:65], v[238:239]
	v_pk_mul_f32 v[66:67], v[66:67], v[240:241]
	global_load_dwordx4 v[234:237], v208, s[20:21] offset:64
	global_load_dwordx4 v[238:241], v208, s[20:21] offset:2112
	s_waitcnt vmcnt(14)
	v_lshlrev_b32_e32 v128, 16, v172
	v_and_b32_e32 v129, 0xffff0000, v172
	v_lshlrev_b32_e32 v130, 16, v173
	v_and_b32_e32 v131, 0xffff0000, v173
	v_lshlrev_b32_e32 v132, 16, v174
	v_and_b32_e32 v133, 0xffff0000, v174
	v_lshlrev_b32_e32 v134, 16, v175
	v_and_b32_e32 v135, 0xffff0000, v175
	v_max_f32_e32 v128, 0xda24260, v128
	v_max_f32_e32 v129, 0xda24260, v129
	v_max_f32_e32 v130, 0xda24260, v130
	v_max_f32_e32 v131, 0xda24260, v131
	v_max_f32_e32 v132, 0xda24260, v132
	v_max_f32_e32 v133, 0xda24260, v133
	v_max_f32_e32 v134, 0xda24260, v134
	v_max_f32_e32 v135, 0xda24260, v135
	v_rcp_f32_e32 v128, v128
	v_rcp_f32_e32 v129, v129
	v_rcp_f32_e32 v130, v130
	v_rcp_f32_e32 v131, v131
	v_rcp_f32_e32 v132, v132
	v_rcp_f32_e32 v133, v133
	v_rcp_f32_e32 v134, v134
	v_rcp_f32_e32 v135, v135
	v_and_b32_e32 v175, 0xffff0000, v171
	v_lshlrev_b32_e32 v174, 16, v171
	v_and_b32_e32 v173, 0xffff0000, v170
	v_lshlrev_b32_e32 v172, 16, v170
	v_and_b32_e32 v171, 0xffff0000, v169
	v_lshlrev_b32_e32 v170, 16, v169
	v_and_b32_e32 v169, 0xffff0000, v168
	v_lshlrev_b32_e32 v168, 16, v168
	v_pk_mul_f32 v[168:169], v[128:129], v[168:169]
	v_pk_mul_f32 v[170:171], v[130:131], v[170:171]
	v_pk_mul_f32 v[172:173], v[132:133], v[172:173]
	v_pk_mul_f32 v[174:175], v[134:135], v[174:175]
	v_pk_mul_f32 v[60:61], v[60:61], v[168:169]
	v_pk_mul_f32 v[62:63], v[62:63], v[170:171]
	v_pk_mul_f32 v[56:57], v[56:57], v[172:173]
	v_pk_mul_f32 v[58:59], v[58:59], v[174:175]
	s_waitcnt vmcnt(12)
	v_lshlrev_b32_e32 v128, 16, v180
	v_and_b32_e32 v129, 0xffff0000, v180
	v_lshlrev_b32_e32 v130, 16, v181
	v_and_b32_e32 v131, 0xffff0000, v181
	v_lshlrev_b32_e32 v132, 16, v182
	v_and_b32_e32 v133, 0xffff0000, v182
	v_lshlrev_b32_e32 v134, 16, v183
	v_and_b32_e32 v135, 0xffff0000, v183
	v_max_f32_e32 v128, 0xda24260, v128
	v_max_f32_e32 v129, 0xda24260, v129
	v_max_f32_e32 v130, 0xda24260, v130
	v_max_f32_e32 v131, 0xda24260, v131
	v_max_f32_e32 v132, 0xda24260, v132
	v_max_f32_e32 v133, 0xda24260, v133
	v_max_f32_e32 v134, 0xda24260, v134
	v_max_f32_e32 v135, 0xda24260, v135
	v_rcp_f32_e32 v128, v128
	v_rcp_f32_e32 v129, v129
	v_rcp_f32_e32 v130, v130
	v_rcp_f32_e32 v131, v131
	v_rcp_f32_e32 v132, v132
	v_rcp_f32_e32 v133, v133
	v_rcp_f32_e32 v134, v134
	v_rcp_f32_e32 v135, v135
	v_and_b32_e32 v183, 0xffff0000, v179
	v_lshlrev_b32_e32 v182, 16, v179
	v_and_b32_e32 v181, 0xffff0000, v178
	v_lshlrev_b32_e32 v180, 16, v178
	v_and_b32_e32 v179, 0xffff0000, v177
	v_lshlrev_b32_e32 v178, 16, v177
	v_and_b32_e32 v177, 0xffff0000, v176
	v_lshlrev_b32_e32 v176, 16, v176
	v_pk_mul_f32 v[176:177], v[128:129], v[176:177]
	v_pk_mul_f32 v[178:179], v[130:131], v[178:179]
	v_pk_mul_f32 v[180:181], v[132:133], v[180:181]
	v_pk_mul_f32 v[182:183], v[134:135], v[182:183]
	v_pk_mul_f32 v[52:53], v[52:53], v[176:177]
	v_pk_mul_f32 v[54:55], v[54:55], v[178:179]
	v_pk_mul_f32 v[48:49], v[48:49], v[180:181]
	v_pk_mul_f32 v[50:51], v[50:51], v[182:183]
	s_waitcnt vmcnt(10)
	v_lshlrev_b32_e32 v128, 16, v188
	v_and_b32_e32 v129, 0xffff0000, v188
	v_lshlrev_b32_e32 v130, 16, v189
	v_and_b32_e32 v131, 0xffff0000, v189
	v_lshlrev_b32_e32 v132, 16, v190
	v_and_b32_e32 v133, 0xffff0000, v190
	v_lshlrev_b32_e32 v134, 16, v191
	v_and_b32_e32 v135, 0xffff0000, v191
	v_max_f32_e32 v128, 0xda24260, v128
	v_max_f32_e32 v129, 0xda24260, v129
	v_max_f32_e32 v130, 0xda24260, v130
	v_max_f32_e32 v131, 0xda24260, v131
	v_max_f32_e32 v132, 0xda24260, v132
	v_max_f32_e32 v133, 0xda24260, v133
	v_max_f32_e32 v134, 0xda24260, v134
	v_max_f32_e32 v135, 0xda24260, v135
	v_rcp_f32_e32 v128, v128
	v_rcp_f32_e32 v129, v129
	v_rcp_f32_e32 v130, v130
	v_rcp_f32_e32 v131, v131
	v_rcp_f32_e32 v132, v132
	v_rcp_f32_e32 v133, v133
	v_rcp_f32_e32 v134, v134
	v_rcp_f32_e32 v135, v135
	v_and_b32_e32 v191, 0xffff0000, v187
	v_lshlrev_b32_e32 v190, 16, v187
	v_and_b32_e32 v189, 0xffff0000, v186
	v_lshlrev_b32_e32 v188, 16, v186
	v_and_b32_e32 v187, 0xffff0000, v185
	v_lshlrev_b32_e32 v186, 16, v185
	v_and_b32_e32 v185, 0xffff0000, v184
	v_lshlrev_b32_e32 v184, 16, v184
	v_pk_mul_f32 v[184:185], v[128:129], v[184:185]
	v_pk_mul_f32 v[186:187], v[130:131], v[186:187]
	v_pk_mul_f32 v[188:189], v[132:133], v[188:189]
	v_pk_mul_f32 v[190:191], v[134:135], v[190:191]
	v_pk_mul_f32 v[44:45], v[44:45], v[184:185]
	v_pk_mul_f32 v[46:47], v[46:47], v[186:187]
	v_pk_mul_f32 v[40:41], v[40:41], v[188:189]
	v_pk_mul_f32 v[42:43], v[42:43], v[190:191]
	s_waitcnt vmcnt(8)
	v_lshlrev_b32_e32 v128, 16, v196
	v_and_b32_e32 v129, 0xffff0000, v196
	v_lshlrev_b32_e32 v130, 16, v197
	v_and_b32_e32 v131, 0xffff0000, v197
	v_lshlrev_b32_e32 v132, 16, v198
	v_and_b32_e32 v133, 0xffff0000, v198
	v_lshlrev_b32_e32 v134, 16, v199
	v_and_b32_e32 v135, 0xffff0000, v199
	v_max_f32_e32 v128, 0xda24260, v128
	v_max_f32_e32 v129, 0xda24260, v129
	v_max_f32_e32 v130, 0xda24260, v130
	v_max_f32_e32 v131, 0xda24260, v131
	v_max_f32_e32 v132, 0xda24260, v132
	v_max_f32_e32 v133, 0xda24260, v133
	v_max_f32_e32 v134, 0xda24260, v134
	v_max_f32_e32 v135, 0xda24260, v135
	v_rcp_f32_e32 v128, v128
	v_rcp_f32_e32 v129, v129
	v_rcp_f32_e32 v130, v130
	v_rcp_f32_e32 v131, v131
	v_rcp_f32_e32 v132, v132
	v_rcp_f32_e32 v133, v133
	v_rcp_f32_e32 v134, v134
	v_rcp_f32_e32 v135, v135
	v_and_b32_e32 v199, 0xffff0000, v195
	v_lshlrev_b32_e32 v198, 16, v195
	v_and_b32_e32 v197, 0xffff0000, v194
	v_lshlrev_b32_e32 v196, 16, v194
	v_and_b32_e32 v195, 0xffff0000, v193
	v_lshlrev_b32_e32 v194, 16, v193
	v_and_b32_e32 v193, 0xffff0000, v192
	v_lshlrev_b32_e32 v192, 16, v192
	v_pk_mul_f32 v[192:193], v[128:129], v[192:193]
	v_pk_mul_f32 v[194:195], v[130:131], v[194:195]
	v_pk_mul_f32 v[196:197], v[132:133], v[196:197]
	v_pk_mul_f32 v[198:199], v[134:135], v[198:199]
	v_pk_mul_f32 v[36:37], v[36:37], v[192:193]
	v_pk_mul_f32 v[38:39], v[38:39], v[194:195]
	v_pk_mul_f32 v[32:33], v[32:33], v[196:197]
	v_pk_mul_f32 v[34:35], v[34:35], v[198:199]
	s_waitcnt vmcnt(6)
	v_lshlrev_b32_e32 v128, 16, v204
	v_and_b32_e32 v129, 0xffff0000, v204
	v_lshlrev_b32_e32 v130, 16, v205
	v_and_b32_e32 v131, 0xffff0000, v205
	v_lshlrev_b32_e32 v132, 16, v206
	v_and_b32_e32 v133, 0xffff0000, v206
	v_lshlrev_b32_e32 v134, 16, v207
	v_and_b32_e32 v135, 0xffff0000, v207
	v_max_f32_e32 v128, 0xda24260, v128
	v_max_f32_e32 v129, 0xda24260, v129
	v_max_f32_e32 v130, 0xda24260, v130
	v_max_f32_e32 v131, 0xda24260, v131
	v_max_f32_e32 v132, 0xda24260, v132
	v_max_f32_e32 v133, 0xda24260, v133
	v_max_f32_e32 v134, 0xda24260, v134
	v_max_f32_e32 v135, 0xda24260, v135
	v_rcp_f32_e32 v128, v128
	v_rcp_f32_e32 v129, v129
	v_rcp_f32_e32 v130, v130
	v_rcp_f32_e32 v131, v131
	v_rcp_f32_e32 v132, v132
	v_rcp_f32_e32 v133, v133
	v_rcp_f32_e32 v134, v134
	v_rcp_f32_e32 v135, v135
	v_and_b32_e32 v207, 0xffff0000, v203
	v_lshlrev_b32_e32 v206, 16, v203
	v_and_b32_e32 v205, 0xffff0000, v202
	v_lshlrev_b32_e32 v204, 16, v202
	v_and_b32_e32 v203, 0xffff0000, v201
	v_lshlrev_b32_e32 v202, 16, v201
	v_and_b32_e32 v201, 0xffff0000, v200
	v_lshlrev_b32_e32 v200, 16, v200
	v_pk_mul_f32 v[200:201], v[128:129], v[200:201]
	v_pk_mul_f32 v[202:203], v[130:131], v[202:203]
	v_pk_mul_f32 v[204:205], v[132:133], v[204:205]
	v_pk_mul_f32 v[206:207], v[134:135], v[206:207]
	v_pk_mul_f32 v[28:29], v[28:29], v[200:201]
	v_pk_mul_f32 v[30:31], v[30:31], v[202:203]
	v_pk_mul_f32 v[24:25], v[24:25], v[204:205]
	v_pk_mul_f32 v[26:27], v[26:27], v[206:207]
	s_waitcnt vmcnt(4)
	v_lshlrev_b32_e32 v128, 16, v222
	v_and_b32_e32 v129, 0xffff0000, v222
	v_lshlrev_b32_e32 v130, 16, v223
	v_and_b32_e32 v131, 0xffff0000, v223
	v_lshlrev_b32_e32 v132, 16, v224
	v_and_b32_e32 v133, 0xffff0000, v224
	v_lshlrev_b32_e32 v134, 16, v225
	v_and_b32_e32 v135, 0xffff0000, v225
	v_max_f32_e32 v128, 0xda24260, v128
	v_max_f32_e32 v129, 0xda24260, v129
	v_max_f32_e32 v130, 0xda24260, v130
	v_max_f32_e32 v131, 0xda24260, v131
	v_max_f32_e32 v132, 0xda24260, v132
	v_max_f32_e32 v133, 0xda24260, v133
	v_max_f32_e32 v134, 0xda24260, v134
	v_max_f32_e32 v135, 0xda24260, v135
	v_rcp_f32_e32 v128, v128
	v_rcp_f32_e32 v129, v129
	v_rcp_f32_e32 v130, v130
	v_rcp_f32_e32 v131, v131
	v_rcp_f32_e32 v132, v132
	v_rcp_f32_e32 v133, v133
	v_rcp_f32_e32 v134, v134
	v_rcp_f32_e32 v135, v135
	v_and_b32_e32 v225, 0xffff0000, v221
	v_lshlrev_b32_e32 v224, 16, v221
	v_and_b32_e32 v223, 0xffff0000, v220
	v_lshlrev_b32_e32 v222, 16, v220
	v_and_b32_e32 v221, 0xffff0000, v219
	v_lshlrev_b32_e32 v220, 16, v219
	v_and_b32_e32 v219, 0xffff0000, v218
	v_lshlrev_b32_e32 v218, 16, v218
	v_pk_mul_f32 v[218:219], v[128:129], v[218:219]
	v_pk_mul_f32 v[220:221], v[130:131], v[220:221]
	v_pk_mul_f32 v[222:223], v[132:133], v[222:223]
	v_pk_mul_f32 v[224:225], v[134:135], v[224:225]
	v_pk_mul_f32 v[20:21], v[20:21], v[218:219]
	v_pk_mul_f32 v[22:23], v[22:23], v[220:221]
	v_pk_mul_f32 v[16:17], v[16:17], v[222:223]
	v_pk_mul_f32 v[18:19], v[18:19], v[224:225]
	s_waitcnt vmcnt(2)
	v_lshlrev_b32_e32 v128, 16, v230
	v_and_b32_e32 v129, 0xffff0000, v230
	v_lshlrev_b32_e32 v130, 16, v231
	v_and_b32_e32 v131, 0xffff0000, v231
	v_lshlrev_b32_e32 v132, 16, v232
	v_and_b32_e32 v133, 0xffff0000, v232
	v_lshlrev_b32_e32 v134, 16, v233
	v_and_b32_e32 v135, 0xffff0000, v233
	v_max_f32_e32 v128, 0xda24260, v128
	v_max_f32_e32 v129, 0xda24260, v129
	v_max_f32_e32 v130, 0xda24260, v130
	v_max_f32_e32 v131, 0xda24260, v131
	v_max_f32_e32 v132, 0xda24260, v132
	v_max_f32_e32 v133, 0xda24260, v133
	v_max_f32_e32 v134, 0xda24260, v134
	v_max_f32_e32 v135, 0xda24260, v135
	v_rcp_f32_e32 v128, v128
	v_rcp_f32_e32 v129, v129
	v_rcp_f32_e32 v130, v130
	v_rcp_f32_e32 v131, v131
	v_rcp_f32_e32 v132, v132
	v_rcp_f32_e32 v133, v133
	v_rcp_f32_e32 v134, v134
	v_rcp_f32_e32 v135, v135
	v_and_b32_e32 v233, 0xffff0000, v229
	v_lshlrev_b32_e32 v232, 16, v229
	v_and_b32_e32 v231, 0xffff0000, v228
	v_lshlrev_b32_e32 v230, 16, v228
	v_and_b32_e32 v229, 0xffff0000, v227
	v_lshlrev_b32_e32 v228, 16, v227
	v_and_b32_e32 v227, 0xffff0000, v226
	v_lshlrev_b32_e32 v226, 16, v226
	v_pk_mul_f32 v[226:227], v[128:129], v[226:227]
	v_pk_mul_f32 v[228:229], v[130:131], v[228:229]
	v_pk_mul_f32 v[230:231], v[132:133], v[230:231]
	v_pk_mul_f32 v[232:233], v[134:135], v[232:233]
	v_pk_mul_f32 v[12:13], v[12:13], v[226:227]
	v_pk_mul_f32 v[14:15], v[14:15], v[228:229]
	v_pk_mul_f32 v[8:9], v[8:9], v[230:231]
	v_pk_mul_f32 v[10:11], v[10:11], v[232:233]
	s_waitcnt vmcnt(0)
	v_lshlrev_b32_e32 v128, 16, v238
	v_and_b32_e32 v129, 0xffff0000, v238
	v_lshlrev_b32_e32 v130, 16, v239
	v_and_b32_e32 v131, 0xffff0000, v239
	v_lshlrev_b32_e32 v132, 16, v240
	v_and_b32_e32 v133, 0xffff0000, v240
	v_lshlrev_b32_e32 v134, 16, v241
	v_and_b32_e32 v135, 0xffff0000, v241
	v_max_f32_e32 v128, 0xda24260, v128
	v_max_f32_e32 v129, 0xda24260, v129
	v_max_f32_e32 v130, 0xda24260, v130
	v_max_f32_e32 v131, 0xda24260, v131
	v_max_f32_e32 v132, 0xda24260, v132
	v_max_f32_e32 v133, 0xda24260, v133
	v_max_f32_e32 v134, 0xda24260, v134
	v_max_f32_e32 v135, 0xda24260, v135
	v_rcp_f32_e32 v128, v128
	v_rcp_f32_e32 v129, v129
	v_rcp_f32_e32 v130, v130
	v_rcp_f32_e32 v131, v131
	v_rcp_f32_e32 v132, v132
	v_rcp_f32_e32 v133, v133
	v_rcp_f32_e32 v134, v134
	v_rcp_f32_e32 v135, v135
	v_and_b32_e32 v241, 0xffff0000, v237
	v_lshlrev_b32_e32 v240, 16, v237
	v_and_b32_e32 v239, 0xffff0000, v236
	v_lshlrev_b32_e32 v238, 16, v236
	v_and_b32_e32 v237, 0xffff0000, v235
	v_lshlrev_b32_e32 v236, 16, v235
	v_and_b32_e32 v235, 0xffff0000, v234
	v_lshlrev_b32_e32 v234, 16, v234
	v_pk_mul_f32 v[234:235], v[128:129], v[234:235]
	v_pk_mul_f32 v[236:237], v[130:131], v[236:237]
	v_pk_mul_f32 v[238:239], v[132:133], v[238:239]
	v_pk_mul_f32 v[240:241], v[134:135], v[240:241]
	v_pk_mul_f32 v[4:5], v[4:5], v[234:235]
	v_pk_mul_f32 v[6:7], v[6:7], v[236:237]
	v_pk_mul_f32 v[0:1], v[0:1], v[238:239]
	v_pk_mul_f32 v[2:3], v[2:3], v[240:241]
	s_branch .LBB0_702
